# hypf2
# baseline (speedup 1.0000x reference)
.LBB0_200:
	v_and_b32_e32 v99, s17, v98
	v_lshl_add_u64 v[92:93], v[90:91], 0, s[24:25]
	s_cmp_lg_u64 s[24:25], 0
	s_cbranch_scc1 .Lhy_nopf
	v_add_co_u32_e32 v246, vcc, 0x26501000, v92
	s_nop 1
	v_addc_co_u32_e32 v247, vcc, 0, v93, vcc
	v_add_co_u32_e32 v244, vcc, 0x1000, v246
	s_nop 1
	v_addc_co_u32_e32 v245, vcc, 0, v247, vcc
	global_load_dword v249, v[246:247], off offset:-4096
	global_load_dword v249, v[246:247], off
	global_load_dword v249, v[244:245], off
	v_add_co_u32_e32 v246, vcc, 0x300000, v246
	s_nop 1
	v_addc_co_u32_e32 v247, vcc, 0, v247, vcc
	v_add_co_u32_e32 v244, vcc, 0x1000, v246
	s_nop 1
	v_addc_co_u32_e32 v245, vcc, 0, v247, vcc
	global_load_dword v249, v[246:247], off offset:-4096
	global_load_dword v249, v[246:247], off
	global_load_dword v249, v[244:245], off
	v_add_co_u32_e32 v246, vcc, 0x300000, v246
	s_nop 1
	v_addc_co_u32_e32 v247, vcc, 0, v247, vcc
	v_add_co_u32_e32 v244, vcc, 0x1000, v246
	s_nop 1
	v_addc_co_u32_e32 v245, vcc, 0, v247, vcc
	global_load_dword v249, v[246:247], off offset:-4096
	global_load_dword v249, v[246:247], off
	global_load_dword v249, v[244:245], off
.Lhy_nopf:
	v_cmp_lt_i32_e64 s[40:41], 0, v99
	s_nop 1
	s_and_b64 s[40:41], s[40:41], 3
	v_mov_b32_e32 v50, 0
	v_mov_b32_e32 v54, 0
	v_mov_b32_e32 v55, 0
	v_mov_b32_e32 v56, 0
	v_mov_b32_e32 v57, 0
	s_and_saveexec_b64 s[42:43], s[40:41]
	s_cbranch_execz .LBB0_202
	v_add_co_u32_e32 v52, vcc, 0x261fd000, v92
	s_nop 1
	v_addc_co_u32_e32 v53, vcc, 0, v93, vcc
	global_load_dwordx4 v[54:57], v[52:53], off
